# nt hint on the P2 gate-tile (G) stores: G is read once much later, in the attention epilogue
# speedup vs baseline: 1.0128x; 1.0128x over previous
.LBB0_741:
	s_lshl_b32 s81, s6, 8
	s_cmpk_lt_i32 s6, 0x80
	s_cselect_b64 s[28:29], -1, 0
	s_cmp_gt_i32 s94, 1
	s_mov_b64 s[6:7], -1
	s_cbranch_scc0 .LBB0_975
	s_cmp_lt_i32 s94, 3
	s_cbranch_scc1 .LBB0_876
	s_cmp_lt_i32 s94, 4
	s_cbranch_scc1 .LBB0_856
	s_cmp_lg_u32 s94, 4
	s_cbranch_scc0 .LBB0_751
	s_andn2_b64 vcc, exec, s[28:29]
	s_cbranch_vccnz .LBB0_750
	s_lshl_b32 s6, s94, 8
	v_readlane_b32 s7, v254, 12
	v_add_u32_e32 v134, s81, v200
	s_or_b32 s6, s6, s7
	v_or_b32_e32 v132, 16, v134
	v_or_b32_e32 v130, 32, v134
	v_or_b32_e32 v128, 48, v134
	s_cmpk_gt_u32 s6, 0x89f
	v_ashrrev_i32_e32 v135, 31, v134
	v_ashrrev_i32_e32 v133, 31, v132
	v_ashrrev_i32_e32 v131, 31, v130
	v_ashrrev_i32_e32 v129, 31, v128
	s_cbranch_scc1 .LBB0_748
	s_lshl_b32 s8, s6, 1
	s_mov_b32 s9, s41
	v_lshl_add_u64 v[140:141], v[162:163], 0, s[8:9]
	v_lshlrev_b64 v[142:143], 11, v[134:135]
	v_lshlrev_b64 v[144:145], 11, v[132:133]
	v_cvt_pk_bf16_f32 v136, v124, v125
	v_cvt_pk_bf16_f32 v137, v126, v127
	v_cvt_pk_bf16_f32 v138, v120, v121
	v_cvt_pk_bf16_f32 v139, v122, v123
	v_lshl_add_u64 v[142:143], v[140:141], 0, v[142:143]
	v_lshl_add_u64 v[144:145], v[140:141], 0, v[144:145]
	global_store_dwordx4 v[142:143], v[136:139], off offset:-2368 nt
	s_mov_b32 s7, 0x3f000
	s_nop 0
	v_cvt_pk_bf16_f32 v136, v108, v109
	v_cvt_pk_bf16_f32 v137, v110, v111
	v_cvt_pk_bf16_f32 v138, v104, v105
	v_cvt_pk_bf16_f32 v139, v106, v107
	global_store_dwordx4 v[144:145], v[136:139], off offset:-2368 nt
	v_lshlrev_b64 v[144:145], 11, v[130:131]
	v_lshl_add_u64 v[144:145], v[140:141], 0, v[144:145]
	v_cvt_pk_bf16_f32 v136, v92, v93
	v_cvt_pk_bf16_f32 v137, v94, v95
	v_cvt_pk_bf16_f32 v138, v88, v89
	v_cvt_pk_bf16_f32 v139, v90, v91
	global_store_dwordx4 v[144:145], v[136:139], off offset:-2368 nt
	v_lshlrev_b64 v[144:145], 11, v[128:129]
	v_lshl_add_u64 v[140:141], v[140:141], 0, v[144:145]
	v_cvt_pk_bf16_f32 v136, v76, v77
	v_cvt_pk_bf16_f32 v137, v78, v79
	v_cvt_pk_bf16_f32 v138, v72, v73
	v_cvt_pk_bf16_f32 v139, v74, v75
	global_store_dwordx4 v[140:141], v[136:139], off offset:-2368 nt
	v_add_co_u32_e32 v140, vcc, s7, v142
	s_mov_b32 s7, 0x47000
	s_nop 0
	v_addc_co_u32_e32 v141, vcc, 0, v143, vcc
	v_cvt_pk_bf16_f32 v136, v60, v61
	v_cvt_pk_bf16_f32 v137, v62, v63
	v_cvt_pk_bf16_f32 v138, v56, v57
	v_cvt_pk_bf16_f32 v139, v58, v59
	global_store_dwordx4 v[140:141], v[136:139], off offset:1728 nt
	v_add_co_u32_e32 v140, vcc, s7, v142
	s_mov_b32 s7, 0x4f000
	s_nop 0
	v_addc_co_u32_e32 v141, vcc, 0, v143, vcc
	v_cvt_pk_bf16_f32 v136, v44, v45
	v_cvt_pk_bf16_f32 v137, v46, v47
	v_cvt_pk_bf16_f32 v138, v40, v41
	v_cvt_pk_bf16_f32 v139, v42, v43
	global_store_dwordx4 v[140:141], v[136:139], off offset:1728 nt
	v_add_co_u32_e32 v140, vcc, s7, v142
	s_nop 0
	v_cvt_pk_bf16_f32 v136, v28, v29
	v_cvt_pk_bf16_f32 v137, v30, v31
	v_cvt_pk_bf16_f32 v138, v24, v25
	v_cvt_pk_bf16_f32 v139, v26, v27
	s_nop 0
	v_addc_co_u32_e32 v141, vcc, 0, v143, vcc
	global_store_dwordx4 v[140:141], v[136:139], off offset:1728 nt
	v_add_co_u32_e32 v140, vcc, 0x57000, v142
	s_nop 0
	v_cvt_pk_bf16_f32 v136, v12, v13
	v_cvt_pk_bf16_f32 v137, v14, v15
	v_cvt_pk_bf16_f32 v138, v8, v9
	v_cvt_pk_bf16_f32 v139, v10, v11
	s_nop 0
	v_addc_co_u32_e32 v141, vcc, 0, v143, vcc
	global_store_dwordx4 v[140:141], v[136:139], off offset:1728 nt
.LBB0_748:
	s_bitset1_b32 s6, 7
	s_cmpk_gt_u32 s6, 0x89f
	s_cbranch_scc1 .LBB0_750
	s_lshl_b32 s6, s6, 1
	s_mov_b32 s7, s41
	v_lshl_add_u64 v[140:141], v[162:163], 0, s[6:7]
	v_lshlrev_b64 v[134:135], 11, v[134:135]
	v_lshlrev_b64 v[132:133], 11, v[132:133]
	v_cvt_pk_bf16_f32 v136, v116, v117
	v_cvt_pk_bf16_f32 v137, v118, v119
	v_lshl_add_u64 v[142:143], v[140:141], 0, v[134:135]
	v_lshl_add_u64 v[132:133], v[140:141], 0, v[132:133]
	v_lshlrev_b64 v[130:131], 11, v[130:131]
	v_cvt_pk_bf16_f32 v138, v112, v113
	v_cvt_pk_bf16_f32 v139, v114, v115
	global_store_dwordx4 v[142:143], v[136:139], off offset:-2368 nt
	v_cvt_pk_bf16_f32 v134, v100, v101
	v_cvt_pk_bf16_f32 v135, v102, v103
	v_lshl_add_u64 v[130:131], v[140:141], 0, v[130:131]
	v_lshlrev_b64 v[128:129], 11, v[128:129]
	v_cvt_pk_bf16_f32 v136, v96, v97
	v_cvt_pk_bf16_f32 v137, v98, v99
	global_store_dwordx4 v[132:133], v[134:137], off offset:-2368 nt
	v_cvt_pk_bf16_f32 v132, v84, v85
	v_cvt_pk_bf16_f32 v133, v86, v87
	v_lshl_add_u64 v[128:129], v[140:141], 0, v[128:129]
	s_mov_b32 s6, 0x3f000
	v_cvt_pk_bf16_f32 v134, v80, v81
	v_cvt_pk_bf16_f32 v135, v82, v83
	global_store_dwordx4 v[130:131], v[132:135], off offset:-2368 nt
	v_cvt_pk_bf16_f32 v130, v68, v69
	v_cvt_pk_bf16_f32 v131, v70, v71
	s_nop 1
	v_cvt_pk_bf16_f32 v132, v64, v65
	v_cvt_pk_bf16_f32 v133, v66, v67
	global_store_dwordx4 v[128:129], v[130:133], off offset:-2368 nt
	v_cvt_pk_bf16_f32 v128, v52, v53
	v_cvt_pk_bf16_f32 v129, v54, v55
	s_nop 1
	v_add_co_u32_e32 v132, vcc, s6, v142
	s_mov_b32 s6, 0x47000
	s_nop 0
	v_addc_co_u32_e32 v133, vcc, 0, v143, vcc
	v_cvt_pk_bf16_f32 v130, v48, v49
	v_cvt_pk_bf16_f32 v131, v50, v51
	global_store_dwordx4 v[132:133], v[128:131], off offset:1728 nt
	v_add_co_u32_e32 v132, vcc, s6, v142
	s_mov_b32 s6, 0x4f000
	s_nop 0
	v_addc_co_u32_e32 v133, vcc, 0, v143, vcc
	v_cvt_pk_bf16_f32 v128, v36, v37
	v_cvt_pk_bf16_f32 v129, v38, v39
	v_cvt_pk_bf16_f32 v130, v32, v33
	v_cvt_pk_bf16_f32 v131, v34, v35
	global_store_dwordx4 v[132:133], v[128:131], off offset:1728 nt
	v_add_co_u32_e32 v132, vcc, s6, v142
	s_nop 0
	v_cvt_pk_bf16_f32 v128, v20, v21
	v_cvt_pk_bf16_f32 v129, v22, v23
	v_cvt_pk_bf16_f32 v130, v16, v17
	v_cvt_pk_bf16_f32 v131, v18, v19
	s_nop 0
	v_addc_co_u32_e32 v133, vcc, 0, v143, vcc
	global_store_dwordx4 v[132:133], v[128:131], off offset:1728 nt
	v_add_co_u32_e32 v132, vcc, 0x57000, v142
	s_nop 0
	v_cvt_pk_bf16_f32 v128, v4, v5
	v_cvt_pk_bf16_f32 v129, v6, v7
	v_cvt_pk_bf16_f32 v130, v0, v1
	v_cvt_pk_bf16_f32 v131, v2, v3
	s_nop 0
	v_addc_co_u32_e32 v133, vcc, 0, v143, vcc
	global_store_dwordx4 v[132:133], v[128:131], off offset:1728 nt
